# stack of the individually neutral edits: NSA selected loop unrolled+lean, window fast path, SGPR-base GEMM loads, b64 accumulator zeroing, DPP layer-0 norm sum, norm-slab register prefetch
# speedup vs baseline: 1.0181x; 1.0181x over previous
; DI int TID8() { int t = threadIdx.x; asm volatile("" : "+v"(t)); return t; }
; DI void gemm8_accum(f32x4 (&acc)[8][4], const bf16_t* a, size_t lda, const bf16_t* b, size_t ldb, int nkb, bf16_t* L,
;                     const bool pre, const bf16_t* an, size_t ldan, const bf16_t* bn, size_t ldbn) {
;   const int tid = TID8(), lane = tid & 63, w = tid >> 6;
;   const int wm = w >> 2, wn = w & 3;
;   const int lrow = tid >> 3, lch = tid & 7;
;   u32x4 ra[4], rb[4];
;   unsigned offa[4], offb[4];
; #pragma unroll
;   for (int i = 0; i < 4; ++i) {
;     offa[i] = (unsigned)(lrow + 64 * i) * (unsigned)lda + (unsigned)(lch * 8);
;     offb[i] = (unsigned)(lrow + 64 * i) * (unsigned)ldb + (unsigned)(lch * 8);
;   }
;   if (!pre) {
;     g8_load1o(ra, a, offa);
;     g8_load1o(rb, b, offb);
;     __syncthreads();
;     g8_store(L, ra, rb, lrow, lch);
;   }
;   g8_load1o(ra, a + 64, offa);
;   g8_load1o(rb, b + 64, offb);
; DI void zero_acc8(f32x4 (&acc)[8][4]) {
; #pragma unroll
;   for (int i = 0; i < 8; ++i)
; #pragma unroll
;     for (int j = 0; j < 4; ++j) acc[i][j] = f32x4{0.f, 0.f, 0.f, 0.f};
.LBB0_133:
	v_lshlrev_b64 v[40:41], 1, v[168:169]
	v_lshlrev_b64 v[42:43], 1, v[166:167]
	v_lshl_add_u64 v[6:7], s[2:3], 0, v[40:41]
	v_lshl_add_u64 v[8:9], s[2:3], 0, v[42:43]
	v_lshlrev_b64 v[44:45], 1, v[0:1]
	global_load_dwordx4 v[18:21], v[6:7], off offset:128
	global_load_dwordx4 v[26:29], v[8:9], off offset:128
	v_lshl_add_u64 v[10:11], s[2:3], 0, v[44:45]
	global_load_dwordx4 v[22:25], v[4:5], off offset:128
	global_load_dwordx4 v[30:33], v[10:11], off offset:128
	global_load_dwordx4 v[6:9], v[2:3], off offset:128
	v_lshl_add_u64 v[2:3], s[0:1], 0, v[40:41]
	s_nop 1
	global_load_dwordx4 v[2:5], v[2:3], off offset:128
	v_lshl_add_u64 v[10:11], s[0:1], 0, v[42:43]
	v_lshl_add_u64 v[14:15], s[0:1], 0, v[44:45]
	global_load_dwordx4 v[10:13], v[10:11], off offset:128
	s_nop 0
	global_load_dwordx4 v[14:17], v[14:15], off offset:128
	v_bfe_u32 v39, v36, 4, 2
	v_lshrrev_b32_e32 v46, 1, v36
	v_bitop3_b32 v46, v46, v39, 7 bitop3:0x6c
	v_lshlrev_b32_e32 v191, 3, v46
	v_lshlrev_b32_e32 v46, 5, v36
	v_bfe_u32 v47, v36, 1, 3
	v_and_b32_e32 v46, 0xffffe000, v46
	v_lshlrev_b32_e32 v36, 6, v36
	s_movk_i32 s0, 0x3c0
	v_and_or_b32 v46, v36, s0, v46
	s_add_u32 s0, s39, s13
	v_add_u32_e32 v34, v35, v34
	v_mov_b32_e32 v35, v1
	s_addc_u32 s1, s40, 0
	v_lshlrev_b64 v[34:35], 1, v[34:35]
	v_lshl_add_u64 v[170:171], s[0:1], 0, v[44:45]
	v_lshl_add_u64 v[172:173], s[0:1], 0, v[42:43]
	v_lshl_add_u64 v[174:175], s[0:1], 0, v[40:41]
	v_lshl_add_u64 v[176:177], s[0:1], 0, v[34:35]
	s_add_i32 s0, s38, s11
	s_add_i32 s0, s0, s12
	s_lshl_b32 s0, s0, 19
	v_readlane_b32 s1, v253, 57
	s_add_u32 s0, s1, s0
	v_readlane_b32 s1, v253, 58
	s_addc_u32 s1, s1, 0
	v_and_b32_e32 v36, 0x33c0, v36
	v_bitop3_b32 v39, v39, v47, 4 bitop3:0x36
	v_lshlrev_b32_e32 v189, 1, v38
	v_lshlrev_b32_e32 v190, 1, v37
	v_lshl_add_u64 v[184:185], s[0:1], 0, v[34:35]
	v_mov_b32_e32 v34, 0
	v_lshlrev_b32_e32 v188, 3, v39
	v_add3_u32 v163, 0, v189, v190
	v_lshl_add_u64 v[178:179], s[0:1], 0, v[44:45]
	v_lshl_add_u64 v[180:181], s[0:1], 0, v[42:43]
	v_lshl_add_u64 v[182:183], s[0:1], 0, v[40:41]
	s_mov_b64 s[0:1], 0
	s_mov_b32 s2, 0
	v_lshlrev_b32_e32 v187, 1, v46
	v_lshlrev_b32_e32 v186, 1, v36
	v_mov_b32_e32 v35, v34
	v_mov_b64_e32 v[36:37], v[34:35]
	v_mov_b64_e32 v[38:39], v[34:35]
	v_mov_b64_e32 v[40:41], v[34:35]
	v_mov_b64_e32 v[42:43], v[34:35]
	v_mov_b64_e32 v[44:45], v[34:35]
	v_mov_b64_e32 v[46:47], v[34:35]
	v_mov_b64_e32 v[48:49], v[34:35]
	v_mov_b64_e32 v[50:51], v[34:35]
	v_mov_b64_e32 v[52:53], v[34:35]
	v_mov_b64_e32 v[54:55], v[34:35]
	v_mov_b64_e32 v[56:57], v[34:35]
	v_mov_b64_e32 v[58:59], v[34:35]
	v_mov_b64_e32 v[60:61], v[34:35]
	v_mov_b64_e32 v[62:63], v[34:35]
	v_mov_b64_e32 v[64:65], v[34:35]
	v_mov_b64_e32 v[66:67], v[34:35]
	v_mov_b64_e32 v[68:69], v[34:35]
	v_mov_b64_e32 v[70:71], v[34:35]
	v_mov_b64_e32 v[72:73], v[34:35]
	v_mov_b64_e32 v[74:75], v[34:35]
	v_mov_b64_e32 v[76:77], v[34:35]
	v_mov_b64_e32 v[78:79], v[34:35]
	v_mov_b64_e32 v[80:81], v[34:35]
	v_mov_b64_e32 v[82:83], v[34:35]
	v_mov_b64_e32 v[84:85], v[34:35]
	v_mov_b64_e32 v[86:87], v[34:35]
	v_mov_b64_e32 v[88:89], v[34:35]
	v_mov_b64_e32 v[90:91], v[34:35]
	v_mov_b64_e32 v[92:93], v[34:35]
	v_mov_b64_e32 v[94:95], v[34:35]
	v_mov_b64_e32 v[96:97], v[34:35]
	v_mov_b64_e32 v[98:99], v[34:35]
	v_mov_b64_e32 v[100:101], v[34:35]
	v_mov_b64_e32 v[102:103], v[34:35]
	v_mov_b64_e32 v[104:105], v[34:35]
	v_mov_b64_e32 v[106:107], v[34:35]
	v_mov_b64_e32 v[108:109], v[34:35]
	v_mov_b64_e32 v[110:111], v[34:35]
	v_mov_b64_e32 v[112:113], v[34:35]
	v_mov_b64_e32 v[114:115], v[34:35]
	v_mov_b64_e32 v[116:117], v[34:35]
	v_mov_b64_e32 v[118:119], v[34:35]
	v_mov_b64_e32 v[120:121], v[34:35]
	v_mov_b64_e32 v[122:123], v[34:35]
	v_mov_b64_e32 v[124:125], v[34:35]
	v_mov_b64_e32 v[126:127], v[34:35]
	v_mov_b64_e32 v[128:129], v[34:35]
	v_mov_b64_e32 v[130:131], v[34:35]
	v_mov_b64_e32 v[132:133], v[34:35]
	v_mov_b64_e32 v[134:135], v[34:35]
	v_mov_b64_e32 v[136:137], v[34:35]
	v_mov_b64_e32 v[138:139], v[34:35]
	v_mov_b64_e32 v[140:141], v[34:35]
	v_mov_b64_e32 v[142:143], v[34:35]
	v_mov_b64_e32 v[144:145], v[34:35]
	v_mov_b64_e32 v[146:147], v[34:35]
	v_mov_b64_e32 v[148:149], v[34:35]
	v_mov_b64_e32 v[150:151], v[34:35]
	v_mov_b64_e32 v[152:153], v[34:35]
	v_mov_b64_e32 v[154:155], v[34:35]
	v_mov_b64_e32 v[156:157], v[34:35]
	v_mov_b64_e32 v[158:159], v[34:35]
	v_mov_b64_e32 v[160:161], v[34:35]
	v_readfirstlane_b32 s52, v184
	v_readfirstlane_b32 s53, v185
	s_sub_u32 s52, s52, 0x40000000
	s_subb_u32 s53, s53, 0
	v_readfirstlane_b32 s56, v176
	v_readfirstlane_b32 s57, v177
	s_sub_u32 s56, s56, 0x40000000
	s_subb_u32 s57, s57, 0
	v_subrev_u32_e32 v185, s52, v184
	v_subrev_u32_e32 v181, s52, v180
	v_subrev_u32_e32 v179, s52, v178
	v_subrev_u32_e32 v183, s52, v182
	v_subrev_u32_e32 v177, s56, v176
	v_subrev_u32_e32 v175, s56, v174
	v_subrev_u32_e32 v173, s56, v172
	v_subrev_u32_e32 v171, s56, v170

; DI int TID8() { int t = threadIdx.x; asm volatile("" : "+v"(t)); return t; }
; DI void gemm8_accum(f32x4 (&acc)[8][4], const bf16_t* a, size_t lda, const bf16_t* b, size_t ldb, int nkb, bf16_t* L,
;                     const bool pre, const bf16_t* an, size_t ldan, const bf16_t* bn, size_t ldbn) {
;   const int tid = TID8(), lane = tid & 63, w = tid >> 6;
;   const int wm = w >> 2, wn = w & 3;
;   const int lrow = tid >> 3, lch = tid & 7;
;   u32x4 ra[4], rb[4];
;   unsigned offa[4], offb[4];
; #pragma unroll
;   for (int i = 0; i < 4; ++i) {
;     offa[i] = (unsigned)(lrow + 64 * i) * (unsigned)lda + (unsigned)(lch * 8);
;     offb[i] = (unsigned)(lrow + 64 * i) * (unsigned)ldb + (unsigned)(lch * 8);
;   }
;   if (!pre) {
;     g8_load1o(ra, a, offa);
;     g8_load1o(rb, b, offb);
;     __syncthreads();
;     g8_store(L, ra, rb, lrow, lch);
;   }
;   g8_load1o(ra, a + 64, offa);
;   g8_load1o(rb, b + 64, offb);
; DI void zero_acc8(f32x4 (&acc)[8][4]) {
; #pragma unroll
;   for (int i = 0; i < 8; ++i)
; #pragma unroll
;     for (int j = 0; j < 4; ++j) acc[i][j] = f32x4{0.f, 0.f, 0.f, 0.f};
.LBB0_777:
	v_lshlrev_b64 v[38:39], 1, v[168:169]
	v_lshl_add_u64 v[6:7], s[2:3], 0, v[38:39]
	v_lshlrev_b64 v[40:41], 1, v[166:167]
	v_lshlrev_b64 v[42:43], 1, v[164:165]
	v_lshl_add_u64 v[8:9], s[2:3], 0, v[40:41]
	global_load_dwordx4 v[18:21], v[6:7], off offset:128
	global_load_dwordx4 v[26:29], v[8:9], off offset:128
	v_lshl_add_u64 v[6:7], s[2:3], 0, v[42:43]
	global_load_dwordx4 v[22:25], v[4:5], off offset:128
	global_load_dwordx4 v[30:33], v[6:7], off offset:128
	global_load_dwordx4 v[14:17], v[2:3], off offset:128
	v_lshl_add_u64 v[2:3], s[0:1], 0, v[38:39]
	s_nop 1
	global_load_dwordx4 v[2:5], v[2:3], off offset:128
	v_lshl_add_u64 v[6:7], s[0:1], 0, v[40:41]
	v_lshl_add_u64 v[10:11], s[0:1], 0, v[42:43]
	global_load_dwordx4 v[6:9], v[6:7], off offset:128
	s_nop 0
	global_load_dwordx4 v[10:13], v[10:11], off offset:128
	s_lshl_b32 s7, s11, 10
	v_bfe_u32 v44, v35, 4, 2
	v_lshrrev_b32_e32 v45, 1, v35
	s_and_b32 s21, s7, 0xc0000
	s_and_b32 s7, s10, 0x60
	v_readlane_b32 s20, v252, 25
	v_bitop3_b32 v45, v45, v44, 7 bitop3:0x6c
	s_or_b32 s7, s20, s7
	s_and_b32 s20, s9, 3
	v_lshlrev_b32_e32 v169, 3, v45
	v_lshlrev_b32_e32 v45, 5, v35
	s_add_i32 s7, s7, s20
	v_bfe_u32 v46, v35, 1, 3
	v_and_b32_e32 v45, 0xffffe000, v45
	v_lshlrev_b32_e32 v35, 6, v35
	s_movk_i32 s0, 0x3c0
	s_lshl_b32 s13, s13, 8
	s_lshl_b32 s6, s12, 9
	s_lshl_b32 s20, s7, 18
	v_and_or_b32 v45, v35, s0, v45
	v_and_b32_e32 v47, 0x33c0, v35
	v_bitop3_b32 v35, v44, v46, 4 bitop3:0x36
	v_readlane_b32 s0, v254, 10
	v_lshlrev_b32_e32 v189, 3, v35
	s_add_u32 s0, s0, s21
	v_readlane_b32 s1, v254, 11
	v_add_u32_e32 v34, v34, v170
	v_mov_b32_e32 v35, v1
	s_addc_u32 s1, s1, 0
	v_lshlrev_b64 v[34:35], 1, v[34:35]
	v_lshl_add_u64 v[172:173], s[0:1], 0, v[42:43]
	v_lshl_add_u64 v[174:175], s[0:1], 0, v[40:41]
	v_lshl_add_u64 v[176:177], s[0:1], 0, v[38:39]
	v_lshl_add_u64 v[178:179], s[0:1], 0, v[34:35]
	v_readlane_b32 s0, v254, 14
	s_add_u32 s0, s0, s20
	v_readlane_b32 s1, v254, 15
	s_addc_u32 s1, s1, 0
	v_lshlrev_b32_e32 v165, 1, v37
	v_lshlrev_b32_e32 v167, 1, v36
	v_lshl_add_u64 v[186:187], s[0:1], 0, v[34:35]
	v_mov_b32_e32 v34, 0
	v_add3_u32 v163, 0, v165, v167
	v_lshl_add_u64 v[180:181], s[0:1], 0, v[42:43]
	v_lshl_add_u64 v[182:183], s[0:1], 0, v[40:41]
	v_lshl_add_u64 v[184:185], s[0:1], 0, v[38:39]
	s_mov_b64 s[0:1], 0
	s_mov_b32 s2, 0
	v_lshlrev_b32_e32 v188, 1, v45
	v_lshlrev_b32_e32 v171, 1, v47
	v_mov_b32_e32 v35, v34
	v_mov_b64_e32 v[36:37], v[34:35]
	v_mov_b64_e32 v[38:39], v[34:35]
	v_mov_b64_e32 v[40:41], v[34:35]
	v_mov_b64_e32 v[42:43], v[34:35]
	v_mov_b64_e32 v[44:45], v[34:35]
	v_mov_b64_e32 v[46:47], v[34:35]
	v_mov_b64_e32 v[48:49], v[34:35]
	v_mov_b64_e32 v[50:51], v[34:35]
	v_mov_b64_e32 v[52:53], v[34:35]
	v_mov_b64_e32 v[54:55], v[34:35]
	v_mov_b64_e32 v[56:57], v[34:35]
	v_mov_b64_e32 v[58:59], v[34:35]
	v_mov_b64_e32 v[60:61], v[34:35]
	v_mov_b64_e32 v[62:63], v[34:35]
	v_mov_b64_e32 v[64:65], v[34:35]
	v_mov_b64_e32 v[66:67], v[34:35]
	v_mov_b64_e32 v[68:69], v[34:35]
	v_mov_b64_e32 v[70:71], v[34:35]
	v_mov_b64_e32 v[72:73], v[34:35]
	v_mov_b64_e32 v[74:75], v[34:35]
	v_mov_b64_e32 v[76:77], v[34:35]
	v_mov_b64_e32 v[78:79], v[34:35]
	v_mov_b64_e32 v[80:81], v[34:35]
	v_mov_b64_e32 v[82:83], v[34:35]
	v_mov_b64_e32 v[84:85], v[34:35]
	v_mov_b64_e32 v[86:87], v[34:35]
	v_mov_b64_e32 v[88:89], v[34:35]
	v_mov_b64_e32 v[90:91], v[34:35]
	v_mov_b64_e32 v[92:93], v[34:35]
	v_mov_b64_e32 v[94:95], v[34:35]
	v_mov_b64_e32 v[96:97], v[34:35]
	v_mov_b64_e32 v[98:99], v[34:35]
	v_mov_b64_e32 v[100:101], v[34:35]
	v_mov_b64_e32 v[102:103], v[34:35]
	v_mov_b64_e32 v[104:105], v[34:35]
	v_mov_b64_e32 v[106:107], v[34:35]
	v_mov_b64_e32 v[108:109], v[34:35]
	v_mov_b64_e32 v[110:111], v[34:35]
	v_mov_b64_e32 v[112:113], v[34:35]
	v_mov_b64_e32 v[114:115], v[34:35]
	v_mov_b64_e32 v[116:117], v[34:35]
	v_mov_b64_e32 v[118:119], v[34:35]
	v_mov_b64_e32 v[120:121], v[34:35]
	v_mov_b64_e32 v[122:123], v[34:35]
	v_mov_b64_e32 v[124:125], v[34:35]
	v_mov_b64_e32 v[126:127], v[34:35]
	v_mov_b64_e32 v[128:129], v[34:35]
	v_mov_b64_e32 v[130:131], v[34:35]
	v_mov_b64_e32 v[132:133], v[34:35]
	v_mov_b64_e32 v[134:135], v[34:35]
	v_mov_b64_e32 v[136:137], v[34:35]
	v_mov_b64_e32 v[138:139], v[34:35]
	v_mov_b64_e32 v[140:141], v[34:35]
	v_mov_b64_e32 v[142:143], v[34:35]
	v_mov_b64_e32 v[144:145], v[34:35]
	v_mov_b64_e32 v[146:147], v[34:35]
	v_mov_b64_e32 v[148:149], v[34:35]
	v_mov_b64_e32 v[150:151], v[34:35]
	v_mov_b64_e32 v[152:153], v[34:35]
	v_mov_b64_e32 v[154:155], v[34:35]
	v_mov_b64_e32 v[156:157], v[34:35]
	v_mov_b64_e32 v[158:159], v[34:35]
	v_mov_b64_e32 v[160:161], v[34:35]
	v_readfirstlane_b32 s52, v186
	v_readfirstlane_b32 s53, v187
	s_sub_u32 s52, s52, 0x40000000
	s_subb_u32 s53, s53, 0
	v_readfirstlane_b32 s56, v178
	v_readfirstlane_b32 s57, v179
	s_sub_u32 s56, s56, 0x40000000
	s_subb_u32 s57, s57, 0
	v_subrev_u32_e32 v187, s52, v186
	v_subrev_u32_e32 v183, s52, v182
	v_subrev_u32_e32 v181, s52, v180
	v_subrev_u32_e32 v185, s52, v184
	v_subrev_u32_e32 v179, s56, v178
	v_subrev_u32_e32 v177, s56, v176
	v_subrev_u32_e32 v175, s56, v174
	v_subrev_u32_e32 v173, s56, v172

; DI int TID8() { int t = threadIdx.x; asm volatile("" : "+v"(t)); return t; }
; DI void gemm8_accum(f32x4 (&acc)[8][4], const bf16_t* a, size_t lda, const bf16_t* b, size_t ldb, int nkb, bf16_t* L,
;                     const bool pre, const bf16_t* an, size_t ldan, const bf16_t* bn, size_t ldbn) {
;   const int tid = TID8(), lane = tid & 63, w = tid >> 6;
;   const int wm = w >> 2, wn = w & 3;
;   const int lrow = tid >> 3, lch = tid & 7;
;   u32x4 ra[4], rb[4];
;   unsigned offa[4], offb[4];
; #pragma unroll
;   for (int i = 0; i < 4; ++i) {
;     offa[i] = (unsigned)(lrow + 64 * i) * (unsigned)lda + (unsigned)(lch * 8);
;     offb[i] = (unsigned)(lrow + 64 * i) * (unsigned)ldb + (unsigned)(lch * 8);
;   }
;   if (!pre) {
;     g8_load1o(ra, a, offa);
;     g8_load1o(rb, b, offb);
;     __syncthreads();
;     g8_store(L, ra, rb, lrow, lch);
;   }
;   g8_load1o(ra, a + 64, offa);
;   g8_load1o(rb, b + 64, offb);
; DI void zero_acc8(f32x4 (&acc)[8][4]) {
; #pragma unroll
;   for (int i = 0; i < 8; ++i)
; #pragma unroll
;     for (int j = 0; j < 4; ++j) acc[i][j] = f32x4{0.f, 0.f, 0.f, 0.f};
.LBB0_829:
	v_lshlrev_b64 v[38:39], 1, v[0:1]
	v_lshlrev_b64 v[40:41], 1, v[176:177]
	v_lshl_add_u64 v[2:3], s[2:3], 0, v[38:39]
	v_lshl_add_u64 v[4:5], s[2:3], 0, v[40:41]
	v_lshlrev_b64 v[42:43], 1, v[174:175]
	v_lshlrev_b64 v[44:45], 1, v[172:173]
	global_load_dwordx4 v[18:21], v[2:3], off offset:3760
	global_load_dwordx4 v[22:25], v[4:5], off offset:3760
	v_lshl_add_u64 v[2:3], s[2:3], 0, v[42:43]
	v_lshl_add_u64 v[4:5], s[2:3], 0, v[44:45]
	v_lshlrev_b64 v[46:47], 1, v[170:171]
	v_lshlrev_b64 v[48:49], 1, v[168:169]
	v_lshlrev_b64 v[50:51], 1, v[166:167]
	v_lshlrev_b64 v[52:53], 1, v[164:165]
	global_load_dwordx4 v[26:29], v[2:3], off offset:3760
	global_load_dwordx4 v[30:33], v[4:5], off offset:3760
	v_lshl_add_u64 v[2:3], s[0:1], 0, v[46:47]
	v_lshl_add_u64 v[4:5], s[0:1], 0, v[48:49]
	v_lshl_add_u64 v[6:7], s[0:1], 0, v[50:51]
	v_lshl_add_u64 v[10:11], s[0:1], 0, v[52:53]
	global_load_dwordx4 v[14:17], v[2:3], off offset:128
	s_nop 0
	global_load_dwordx4 v[2:5], v[4:5], off offset:128
	s_nop 0
	global_load_dwordx4 v[6:9], v[6:7], off offset:128
	s_nop 0
	global_load_dwordx4 v[10:13], v[10:11], off offset:128
	v_bfe_u32 v37, v34, 4, 2
	v_lshrrev_b32_e32 v54, 1, v34
	v_bitop3_b32 v54, v54, v37, 7 bitop3:0x6c
	s_lshr_b32 s7, s13, 2
	s_lshl_b32 s6, s12, 8
	s_and_b32 s12, s10, 0x60
	v_readlane_b32 s20, v252, 25
	v_lshlrev_b32_e32 v169, 3, v54
	v_lshlrev_b32_e32 v54, 5, v34
	s_and_b32 s7, s7, 3
	s_or_b32 s12, s20, s12
	s_and_b32 s20, s9, 3
	v_bfe_u32 v55, v34, 1, 3
	v_and_b32_e32 v54, 0xffffe000, v54
	v_lshlrev_b32_e32 v34, 6, v34
	s_movk_i32 s0, 0x3c0
	s_lshl_b32 s7, s7, 19
	s_add_i32 s12, s12, s20
	v_and_or_b32 v54, v34, s0, v54
	v_readlane_b32 s0, v254, 24
	s_add_u32 s0, s0, s7
	v_readlane_b32 s1, v254, 25
	s_addc_u32 s1, s1, 0
	s_mul_i32 s12, s12, 0x2a3000
	v_lshl_add_u64 v[178:179], s[0:1], 0, v[52:53]
	v_lshl_add_u64 v[180:181], s[0:1], 0, v[50:51]
	v_lshl_add_u64 v[182:183], s[0:1], 0, v[48:49]
	v_lshl_add_u64 v[184:185], s[0:1], 0, v[46:47]
	v_readlane_b32 s0, v254, 26
	v_and_b32_e32 v56, 0x33c0, v34
	v_bitop3_b32 v34, v37, v55, 4 bitop3:0x36
	s_add_u32 s0, s0, s12
	v_readlane_b32 s1, v254, 27
	v_lshlrev_b32_e32 v205, 3, v34
	v_lshlrev_b32_e32 v165, 1, v36
	v_lshlrev_b32_e32 v167, 1, v35
	s_addc_u32 s1, s1, 0
	v_mov_b32_e32 v34, 0
	v_add3_u32 v163, 0, v165, v167
	v_lshl_add_u64 v[186:187], s[0:1], 0, v[44:45]
	v_lshl_add_u64 v[188:189], s[0:1], 0, v[42:43]
	v_lshl_add_u64 v[190:191], s[0:1], 0, v[40:41]
	v_lshl_add_u64 v[192:193], s[0:1], 0, v[38:39]
	s_mov_b64 s[0:1], 0
	s_mov_b32 s2, 0
	v_lshlrev_b32_e32 v195, 1, v54
	v_lshlrev_b32_e32 v194, 1, v56
	v_mov_b32_e32 v35, v34
	v_mov_b64_e32 v[36:37], v[34:35]
	v_mov_b64_e32 v[38:39], v[34:35]
	v_mov_b64_e32 v[40:41], v[34:35]
	v_mov_b64_e32 v[42:43], v[34:35]
	v_mov_b64_e32 v[44:45], v[34:35]
	v_mov_b64_e32 v[46:47], v[34:35]
	v_mov_b64_e32 v[48:49], v[34:35]
	v_mov_b64_e32 v[50:51], v[34:35]
	v_mov_b64_e32 v[52:53], v[34:35]
	v_mov_b64_e32 v[54:55], v[34:35]
	v_mov_b64_e32 v[56:57], v[34:35]
	v_mov_b64_e32 v[58:59], v[34:35]
	v_mov_b64_e32 v[60:61], v[34:35]
	v_mov_b64_e32 v[62:63], v[34:35]
	v_mov_b64_e32 v[64:65], v[34:35]
	v_mov_b64_e32 v[66:67], v[34:35]
	v_mov_b64_e32 v[68:69], v[34:35]
	v_mov_b64_e32 v[70:71], v[34:35]
	v_mov_b64_e32 v[72:73], v[34:35]
	v_mov_b64_e32 v[74:75], v[34:35]
	v_mov_b64_e32 v[76:77], v[34:35]
	v_mov_b64_e32 v[78:79], v[34:35]
	v_mov_b64_e32 v[80:81], v[34:35]
	v_mov_b64_e32 v[82:83], v[34:35]
	v_mov_b64_e32 v[84:85], v[34:35]
	v_mov_b64_e32 v[86:87], v[34:35]
	v_mov_b64_e32 v[88:89], v[34:35]
	v_mov_b64_e32 v[90:91], v[34:35]
	v_mov_b64_e32 v[92:93], v[34:35]
	v_mov_b64_e32 v[94:95], v[34:35]
	v_mov_b64_e32 v[96:97], v[34:35]
	v_mov_b64_e32 v[98:99], v[34:35]
	v_mov_b64_e32 v[100:101], v[34:35]
	v_mov_b64_e32 v[102:103], v[34:35]
	v_mov_b64_e32 v[104:105], v[34:35]
	v_mov_b64_e32 v[106:107], v[34:35]
	v_mov_b64_e32 v[108:109], v[34:35]
	v_mov_b64_e32 v[110:111], v[34:35]
	v_mov_b64_e32 v[112:113], v[34:35]
	v_mov_b64_e32 v[114:115], v[34:35]
	v_mov_b64_e32 v[116:117], v[34:35]
	v_mov_b64_e32 v[118:119], v[34:35]
	v_mov_b64_e32 v[120:121], v[34:35]
	v_mov_b64_e32 v[122:123], v[34:35]
	v_mov_b64_e32 v[124:125], v[34:35]
	v_mov_b64_e32 v[126:127], v[34:35]
	v_mov_b64_e32 v[128:129], v[34:35]
	v_mov_b64_e32 v[130:131], v[34:35]
	v_mov_b64_e32 v[132:133], v[34:35]
	v_mov_b64_e32 v[134:135], v[34:35]
	v_mov_b64_e32 v[136:137], v[34:35]
	v_mov_b64_e32 v[138:139], v[34:35]
	v_mov_b64_e32 v[140:141], v[34:35]
	v_mov_b64_e32 v[142:143], v[34:35]
	v_mov_b64_e32 v[144:145], v[34:35]
	v_mov_b64_e32 v[146:147], v[34:35]
	v_mov_b64_e32 v[148:149], v[34:35]
	v_mov_b64_e32 v[150:151], v[34:35]
	v_mov_b64_e32 v[152:153], v[34:35]
	v_mov_b64_e32 v[154:155], v[34:35]
	v_mov_b64_e32 v[156:157], v[34:35]
	v_mov_b64_e32 v[158:159], v[34:35]
	v_mov_b64_e32 v[160:161], v[34:35]
	v_readfirstlane_b32 s52, v192
	v_readfirstlane_b32 s53, v193
	s_sub_u32 s52, s52, 0x40000000
	s_subb_u32 s53, s53, 0
	v_readfirstlane_b32 s56, v184
	v_readfirstlane_b32 s57, v185
	s_sub_u32 s56, s56, 0x40000000
	s_subb_u32 s57, s57, 0
	v_subrev_u32_e32 v193, s52, v192
	v_subrev_u32_e32 v191, s52, v190
	v_subrev_u32_e32 v189, s52, v188
	v_subrev_u32_e32 v187, s52, v186
	v_subrev_u32_e32 v185, s56, v184
	v_subrev_u32_e32 v183, s56, v182
	v_subrev_u32_e32 v181, s56, v180
	v_subrev_u32_e32 v179, s56, v178

; DI int TID8() { int t = threadIdx.x; asm volatile("" : "+v"(t)); return t; }
; DI void gemm8_accum(f32x4 (&acc)[8][4], const bf16_t* a, size_t lda, const bf16_t* b, size_t ldb, int nkb, bf16_t* L,
;                     const bool pre, const bf16_t* an, size_t ldan, const bf16_t* bn, size_t ldbn) {
;   const int tid = TID8(), lane = tid & 63, w = tid >> 6;
;   const int wm = w >> 2, wn = w & 3;
;   const int lrow = tid >> 3, lch = tid & 7;
;   u32x4 ra[4], rb[4];
;   unsigned offa[4], offb[4];
; #pragma unroll
;   for (int i = 0; i < 4; ++i) {
;     offa[i] = (unsigned)(lrow + 64 * i) * (unsigned)lda + (unsigned)(lch * 8);
;     offb[i] = (unsigned)(lrow + 64 * i) * (unsigned)ldb + (unsigned)(lch * 8);
;   }
;   if (!pre) {
;     g8_load1o(ra, a, offa);
;     g8_load1o(rb, b, offb);
;     __syncthreads();
;     g8_store(L, ra, rb, lrow, lch);
;   }
;   g8_load1o(ra, a + 64, offa);
;   g8_load1o(rb, b + 64, offb);
; DI void zero_acc8(f32x4 (&acc)[8][4]) {
; #pragma unroll
;   for (int i = 0; i < 8; ++i)
; #pragma unroll
;     for (int j = 0; j < 4; ++j) acc[i][j] = f32x4{0.f, 0.f, 0.f, 0.f};
.LBB0_891:
	v_lshlrev_b64 v[40:41], 1, v[168:169]
	v_lshl_add_u64 v[6:7], s[2:3], 0, v[40:41]
	v_lshlrev_b64 v[42:43], 1, v[166:167]
	v_lshlrev_b64 v[44:45], 1, v[0:1]
	v_lshl_add_u64 v[8:9], s[2:3], 0, v[42:43]
	global_load_dwordx4 v[18:21], v[6:7], off offset:128
	global_load_dwordx4 v[26:29], v[8:9], off offset:128
	v_lshl_add_u64 v[6:7], s[2:3], 0, v[44:45]
	global_load_dwordx4 v[22:25], v[4:5], off offset:128
	global_load_dwordx4 v[30:33], v[6:7], off offset:128
	global_load_dwordx4 v[14:17], v[2:3], off offset:128
	v_lshl_add_u64 v[2:3], s[0:1], 0, v[40:41]
	s_nop 1
	global_load_dwordx4 v[2:5], v[2:3], off offset:128
	v_lshl_add_u64 v[6:7], s[0:1], 0, v[42:43]
	v_lshl_add_u64 v[10:11], s[0:1], 0, v[44:45]
	global_load_dwordx4 v[6:9], v[6:7], off offset:128
	s_nop 0
	global_load_dwordx4 v[10:13], v[10:11], off offset:128
	v_bfe_u32 v39, v36, 4, 2
	v_lshrrev_b32_e32 v46, 1, v36
	v_readlane_b32 s7, v252, 25
	v_bitop3_b32 v46, v46, v39, 7 bitop3:0x6c
	s_or_b32 s7, s7, s12
	s_and_b32 s12, s9, 3
	v_lshlrev_b32_e32 v191, 3, v46
	v_lshlrev_b32_e32 v46, 5, v36
	s_lshl_b32 s6, s10, 11
	s_add_i32 s7, s7, s12
	v_bfe_u32 v47, v36, 1, 3
	v_and_b32_e32 v46, 0xffffe000, v46
	v_lshlrev_b32_e32 v36, 6, v36
	s_movk_i32 s0, 0x3c0
	s_and_b32 s6, s6, 0x780000
	s_lshl_b32 s7, s7, 19
	v_and_or_b32 v46, v36, s0, v46
	v_readlane_b32 s0, v254, 28
	s_add_u32 s0, s0, s6
	v_readlane_b32 s1, v254, 29
	v_add_u32_e32 v34, v35, v34
	v_mov_b32_e32 v35, v1
	s_addc_u32 s1, s1, 0
	v_lshlrev_b64 v[34:35], 1, v[34:35]
	v_lshl_add_u64 v[170:171], s[0:1], 0, v[44:45]
	v_lshl_add_u64 v[172:173], s[0:1], 0, v[42:43]
	v_lshl_add_u64 v[174:175], s[0:1], 0, v[40:41]
	v_lshl_add_u64 v[176:177], s[0:1], 0, v[34:35]
	v_readlane_b32 s0, v253, 57
	s_add_u32 s0, s0, s7
	v_readlane_b32 s1, v253, 58
	s_addc_u32 s1, s1, 0
	v_and_b32_e32 v36, 0x33c0, v36
	v_bitop3_b32 v39, v39, v47, 4 bitop3:0x36
	v_lshlrev_b32_e32 v189, 1, v38
	v_lshlrev_b32_e32 v190, 1, v37
	v_lshl_add_u64 v[184:185], s[0:1], 0, v[34:35]
	v_mov_b32_e32 v34, 0
	v_lshlrev_b32_e32 v188, 3, v39
	v_add3_u32 v163, 0, v189, v190
	v_lshl_add_u64 v[178:179], s[0:1], 0, v[44:45]
	v_lshl_add_u64 v[180:181], s[0:1], 0, v[42:43]
	v_lshl_add_u64 v[182:183], s[0:1], 0, v[40:41]
	s_mov_b64 s[0:1], 0
	s_mov_b32 s2, 0
	v_lshlrev_b32_e32 v187, 1, v46
	v_lshlrev_b32_e32 v186, 1, v36
	v_mov_b32_e32 v35, v34
	v_mov_b64_e32 v[36:37], v[34:35]
	v_mov_b64_e32 v[38:39], v[34:35]
	v_mov_b64_e32 v[40:41], v[34:35]
	v_mov_b64_e32 v[42:43], v[34:35]
	v_mov_b64_e32 v[44:45], v[34:35]
	v_mov_b64_e32 v[46:47], v[34:35]
	v_mov_b64_e32 v[48:49], v[34:35]
	v_mov_b64_e32 v[50:51], v[34:35]
	v_mov_b64_e32 v[52:53], v[34:35]
	v_mov_b64_e32 v[54:55], v[34:35]
	v_mov_b64_e32 v[56:57], v[34:35]
	v_mov_b64_e32 v[58:59], v[34:35]
	v_mov_b64_e32 v[60:61], v[34:35]
	v_mov_b64_e32 v[62:63], v[34:35]
	v_mov_b64_e32 v[64:65], v[34:35]
	v_mov_b64_e32 v[66:67], v[34:35]
	v_mov_b64_e32 v[68:69], v[34:35]
	v_mov_b64_e32 v[70:71], v[34:35]
	v_mov_b64_e32 v[72:73], v[34:35]
	v_mov_b64_e32 v[74:75], v[34:35]
	v_mov_b64_e32 v[76:77], v[34:35]
	v_mov_b64_e32 v[78:79], v[34:35]
	v_mov_b64_e32 v[80:81], v[34:35]
	v_mov_b64_e32 v[82:83], v[34:35]
	v_mov_b64_e32 v[84:85], v[34:35]
	v_mov_b64_e32 v[86:87], v[34:35]
	v_mov_b64_e32 v[88:89], v[34:35]
	v_mov_b64_e32 v[90:91], v[34:35]
	v_mov_b64_e32 v[92:93], v[34:35]
	v_mov_b64_e32 v[94:95], v[34:35]
	v_mov_b64_e32 v[96:97], v[34:35]
	v_mov_b64_e32 v[98:99], v[34:35]
	v_mov_b64_e32 v[100:101], v[34:35]
	v_mov_b64_e32 v[102:103], v[34:35]
	v_mov_b64_e32 v[104:105], v[34:35]
	v_mov_b64_e32 v[106:107], v[34:35]
	v_mov_b64_e32 v[108:109], v[34:35]
	v_mov_b64_e32 v[110:111], v[34:35]
	v_mov_b64_e32 v[112:113], v[34:35]
	v_mov_b64_e32 v[114:115], v[34:35]
	v_mov_b64_e32 v[116:117], v[34:35]
	v_mov_b64_e32 v[118:119], v[34:35]
	v_mov_b64_e32 v[120:121], v[34:35]
	v_mov_b64_e32 v[122:123], v[34:35]
	v_mov_b64_e32 v[124:125], v[34:35]
	v_mov_b64_e32 v[126:127], v[34:35]
	v_mov_b64_e32 v[128:129], v[34:35]
	v_mov_b64_e32 v[130:131], v[34:35]
	v_mov_b64_e32 v[132:133], v[34:35]
	v_mov_b64_e32 v[134:135], v[34:35]
	v_mov_b64_e32 v[136:137], v[34:35]
	v_mov_b64_e32 v[138:139], v[34:35]
	v_mov_b64_e32 v[140:141], v[34:35]
	v_mov_b64_e32 v[142:143], v[34:35]
	v_mov_b64_e32 v[144:145], v[34:35]
	v_mov_b64_e32 v[146:147], v[34:35]
	v_mov_b64_e32 v[148:149], v[34:35]
	v_mov_b64_e32 v[150:151], v[34:35]
	v_mov_b64_e32 v[152:153], v[34:35]
	v_mov_b64_e32 v[154:155], v[34:35]
	v_mov_b64_e32 v[156:157], v[34:35]
	v_mov_b64_e32 v[158:159], v[34:35]
	v_mov_b64_e32 v[160:161], v[34:35]
	v_readfirstlane_b32 s52, v184
	v_readfirstlane_b32 s53, v185
	s_sub_u32 s52, s52, 0x40000000
	s_subb_u32 s53, s53, 0
	v_readfirstlane_b32 s56, v176
	v_readfirstlane_b32 s57, v177
	s_sub_u32 s56, s56, 0x40000000
	s_subb_u32 s57, s57, 0
	v_subrev_u32_e32 v185, s52, v184
	v_subrev_u32_e32 v181, s52, v180
	v_subrev_u32_e32 v179, s52, v178
	v_subrev_u32_e32 v183, s52, v182
	v_subrev_u32_e32 v177, s56, v176
	v_subrev_u32_e32 v175, s56, v174
	v_subrev_u32_e32 v173, s56, v172
	v_subrev_u32_e32 v171, s56, v170

; DI int TID8() { int t = threadIdx.x; asm volatile("" : "+v"(t)); return t; }
; DI void gemm8_accum(f32x4 (&acc)[8][4], const bf16_t* a, size_t lda, const bf16_t* b, size_t ldb, int nkb, bf16_t* L,
;                     const bool pre, const bf16_t* an, size_t ldan, const bf16_t* bn, size_t ldbn) {
;   const int tid = TID8(), lane = tid & 63, w = tid >> 6;
;   const int wm = w >> 2, wn = w & 3;
;   const int lrow = tid >> 3, lch = tid & 7;
;   u32x4 ra[4], rb[4];
;   unsigned offa[4], offb[4];
; #pragma unroll
;   for (int i = 0; i < 4; ++i) {
;     offa[i] = (unsigned)(lrow + 64 * i) * (unsigned)lda + (unsigned)(lch * 8);
;     offb[i] = (unsigned)(lrow + 64 * i) * (unsigned)ldb + (unsigned)(lch * 8);
;   }
;   if (!pre) {
;     g8_load1o(ra, a, offa);
;     g8_load1o(rb, b, offb);
;     __syncthreads();
;     g8_store(L, ra, rb, lrow, lch);
;   }
;   g8_load1o(ra, a + 64, offa);
;   g8_load1o(rb, b + 64, offb);
; DI void zero_acc8(f32x4 (&acc)[8][4]) {
; #pragma unroll
;   for (int i = 0; i < 8; ++i)
; #pragma unroll
;     for (int j = 0; j < 4; ++j) acc[i][j] = f32x4{0.f, 0.f, 0.f, 0.f};
.LBB0_941:
	v_lshlrev_b64 v[40:41], 1, v[168:169]
	v_lshl_add_u64 v[6:7], s[2:3], 0, v[40:41]
	v_lshlrev_b64 v[42:43], 1, v[166:167]
	v_lshlrev_b64 v[44:45], 1, v[0:1]
	v_lshl_add_u64 v[8:9], s[2:3], 0, v[42:43]
	global_load_dwordx4 v[18:21], v[6:7], off offset:128
	global_load_dwordx4 v[26:29], v[8:9], off offset:128
	v_lshl_add_u64 v[6:7], s[2:3], 0, v[44:45]
	global_load_dwordx4 v[22:25], v[4:5], off offset:128
	global_load_dwordx4 v[30:33], v[6:7], off offset:128
	global_load_dwordx4 v[14:17], v[2:3], off offset:128
	v_lshl_add_u64 v[2:3], s[0:1], 0, v[40:41]
	s_nop 1
	global_load_dwordx4 v[2:5], v[2:3], off offset:128
	v_lshl_add_u64 v[6:7], s[0:1], 0, v[42:43]
	v_lshl_add_u64 v[10:11], s[0:1], 0, v[44:45]
	global_load_dwordx4 v[6:9], v[6:7], off offset:128
	s_nop 0
	global_load_dwordx4 v[10:13], v[10:11], off offset:128
	v_bfe_u32 v39, v36, 4, 2
	v_lshrrev_b32_e32 v46, 1, v36
	s_lshl_b32 s6, s12, 8
	s_and_b32 s12, s10, 0x60
	v_readlane_b32 s20, v252, 25
	v_bitop3_b32 v46, v46, v39, 7 bitop3:0x6c
	s_lshr_b32 s7, s13, 2
	s_or_b32 s12, s20, s12
	s_and_b32 s20, s9, 3
	v_lshlrev_b32_e32 v191, 3, v46
	v_lshlrev_b32_e32 v46, 5, v36
	s_and_b32 s7, s7, 3
	s_add_i32 s12, s12, s20
	v_bfe_u32 v47, v36, 1, 3
	v_and_b32_e32 v46, 0xffffe000, v46
	v_lshlrev_b32_e32 v36, 6, v36
	s_movk_i32 s0, 0x3c0
	s_lshl_b32 s7, s7, 21
	s_lshl_b32 s12, s12, 21
	v_and_or_b32 v46, v36, s0, v46
	v_readlane_b32 s0, v254, 30
	s_add_u32 s0, s0, s7
	v_readlane_b32 s1, v254, 31
	v_add_u32_e32 v34, v35, v34
	v_mov_b32_e32 v35, v1
	s_addc_u32 s1, s1, 0
	v_lshlrev_b64 v[34:35], 1, v[34:35]
	v_lshl_add_u64 v[170:171], s[0:1], 0, v[44:45]
	v_lshl_add_u64 v[172:173], s[0:1], 0, v[42:43]
	v_lshl_add_u64 v[174:175], s[0:1], 0, v[40:41]
	v_lshl_add_u64 v[176:177], s[0:1], 0, v[34:35]
	v_readlane_b32 s0, v254, 32
	s_add_u32 s0, s0, s12
	v_readlane_b32 s1, v254, 33
	s_addc_u32 s1, s1, 0
	v_and_b32_e32 v36, 0x33c0, v36
	v_bitop3_b32 v39, v39, v47, 4 bitop3:0x36
	v_lshlrev_b32_e32 v189, 1, v38
	v_lshlrev_b32_e32 v190, 1, v37
	v_lshl_add_u64 v[184:185], s[0:1], 0, v[34:35]
	v_mov_b32_e32 v34, 0
	v_lshlrev_b32_e32 v188, 3, v39
	v_add3_u32 v163, 0, v189, v190
	v_lshl_add_u64 v[178:179], s[0:1], 0, v[44:45]
	v_lshl_add_u64 v[180:181], s[0:1], 0, v[42:43]
	v_lshl_add_u64 v[182:183], s[0:1], 0, v[40:41]
	s_mov_b64 s[0:1], 0
	s_mov_b32 s2, 0
	v_lshlrev_b32_e32 v187, 1, v46
	v_lshlrev_b32_e32 v186, 1, v36
	v_mov_b32_e32 v35, v34
	v_mov_b64_e32 v[36:37], v[34:35]
	v_mov_b64_e32 v[38:39], v[34:35]
	v_mov_b64_e32 v[40:41], v[34:35]
	v_mov_b64_e32 v[42:43], v[34:35]
	v_mov_b64_e32 v[44:45], v[34:35]
	v_mov_b64_e32 v[46:47], v[34:35]
	v_mov_b64_e32 v[48:49], v[34:35]
	v_mov_b64_e32 v[50:51], v[34:35]
	v_mov_b64_e32 v[52:53], v[34:35]
	v_mov_b64_e32 v[54:55], v[34:35]
	v_mov_b64_e32 v[56:57], v[34:35]
	v_mov_b64_e32 v[58:59], v[34:35]
	v_mov_b64_e32 v[60:61], v[34:35]
	v_mov_b64_e32 v[62:63], v[34:35]
	v_mov_b64_e32 v[64:65], v[34:35]
	v_mov_b64_e32 v[66:67], v[34:35]
	v_mov_b64_e32 v[68:69], v[34:35]
	v_mov_b64_e32 v[70:71], v[34:35]
	v_mov_b64_e32 v[72:73], v[34:35]
	v_mov_b64_e32 v[74:75], v[34:35]
	v_mov_b64_e32 v[76:77], v[34:35]
	v_mov_b64_e32 v[78:79], v[34:35]
	v_mov_b64_e32 v[80:81], v[34:35]
	v_mov_b64_e32 v[82:83], v[34:35]
	v_mov_b64_e32 v[84:85], v[34:35]
	v_mov_b64_e32 v[86:87], v[34:35]
	v_mov_b64_e32 v[88:89], v[34:35]
	v_mov_b64_e32 v[90:91], v[34:35]
	v_mov_b64_e32 v[92:93], v[34:35]
	v_mov_b64_e32 v[94:95], v[34:35]
	v_mov_b64_e32 v[96:97], v[34:35]
	v_mov_b64_e32 v[98:99], v[34:35]
	v_mov_b64_e32 v[100:101], v[34:35]
	v_mov_b64_e32 v[102:103], v[34:35]
	v_mov_b64_e32 v[104:105], v[34:35]
	v_mov_b64_e32 v[106:107], v[34:35]
	v_mov_b64_e32 v[108:109], v[34:35]
	v_mov_b64_e32 v[110:111], v[34:35]
	v_mov_b64_e32 v[112:113], v[34:35]
	v_mov_b64_e32 v[114:115], v[34:35]
	v_mov_b64_e32 v[116:117], v[34:35]
	v_mov_b64_e32 v[118:119], v[34:35]
	v_mov_b64_e32 v[120:121], v[34:35]
	v_mov_b64_e32 v[122:123], v[34:35]
	v_mov_b64_e32 v[124:125], v[34:35]
	v_mov_b64_e32 v[126:127], v[34:35]
	v_mov_b64_e32 v[128:129], v[34:35]
	v_mov_b64_e32 v[130:131], v[34:35]
	v_mov_b64_e32 v[132:133], v[34:35]
	v_mov_b64_e32 v[134:135], v[34:35]
	v_mov_b64_e32 v[136:137], v[34:35]
	v_mov_b64_e32 v[138:139], v[34:35]
	v_mov_b64_e32 v[140:141], v[34:35]
	v_mov_b64_e32 v[142:143], v[34:35]
	v_mov_b64_e32 v[144:145], v[34:35]
	v_mov_b64_e32 v[146:147], v[34:35]
	v_mov_b64_e32 v[148:149], v[34:35]
	v_mov_b64_e32 v[150:151], v[34:35]
	v_mov_b64_e32 v[152:153], v[34:35]
	v_mov_b64_e32 v[154:155], v[34:35]
	v_mov_b64_e32 v[156:157], v[34:35]
	v_mov_b64_e32 v[158:159], v[34:35]
	v_mov_b64_e32 v[160:161], v[34:35]
	v_readfirstlane_b32 s52, v184
	v_readfirstlane_b32 s53, v185
	s_sub_u32 s52, s52, 0x40000000
	s_subb_u32 s53, s53, 0
	v_readfirstlane_b32 s56, v176
	v_readfirstlane_b32 s57, v177
	s_sub_u32 s56, s56, 0x40000000
	s_subb_u32 s57, s57, 0
	v_subrev_u32_e32 v185, s52, v184
	v_subrev_u32_e32 v181, s52, v180
	v_subrev_u32_e32 v179, s52, v178
	v_subrev_u32_e32 v183, s52, v182
	v_subrev_u32_e32 v177, s56, v176
	v_subrev_u32_e32 v175, s56, v174
	v_subrev_u32_e32 v173, s56, v172
	v_subrev_u32_e32 v171, s56, v170
